# attention: output-gate rows prefetched during the last loop iteration of each latent unit instead of at the epilogue start
# speedup vs baseline: 1.0056x; 1.0056x over previous
; #define LAS __attribute__((address_space(3)))
; __device__ __forceinline__ bf16_t f2bf(float f) { return (bf16_t)(cvtpk(f, 0.f) & 0xffffu); }
; __device__ __forceinline__ float frcp(float x) { return __builtin_amdgcn_rcpf(x); }
; __device__ __forceinline__ int crow(int r, int hi) { return (r & 3) + 8 * (r >> 2) + 4 * hi; }
; __device__ __forceinline__ void attn_unit(LAS char* lds, const bf16_t* Qp, const bf16_t* KVp, const bf16_t* KRp, int ntiles, bf16_t* Yp, bool dry) {
;     ...
;     lsum += __shfl_xor(lsum, 32);
;     if (hi == 0) wsf[r32] = frcp(lsum);
;     asm volatile("s_waitcnt lgkmcnt(0)" ::: "memory");
;     LAS char* ost = lds + A_OST + wid * (32 * A_OP);
; #pragma unroll
;     for (int k = 0; k < 4; ++k) { const f32x4 a = *(const LAS f32x4*)(wsf + 8 * k + 4 * hi);
; #pragma unroll
;         for (int j = 0; j < 4; ++j) { const int r = 4 * k + j; LAS bf16_t* op = (LAS bf16_t*)(ost + crow(r, hi) * A_OP) + r32;
;             op[0] = f2bf(o0[r] * a[j]); op[32] = f2bf(o1[r] * a[j]); } }
;     asm volatile("s_waitcnt lgkmcnt(0)" ::: "memory");
; #pragma unroll
;     for (int i = 0; i < 4; ++i) { const int id = lane + 64 * i, row = id >> 3, ch = id & 7;
;         const u32x4 ov = *(const LAS u32x4*)(ost + row * A_OP + ch * 16);
;         bf16_t* yp = Yp + (size_t)(wid * 32 + row) * ZP + ch * 8;
;         if (!dry) { const u32x4 gv = *(const u32x4*)yp; u32x4 w;
.LBB0_781:
	s_or_b64 exec, exec, s[0:1]
	s_mulk_i32 s28, 0x1c00
	s_mul_hi_u32 s0, s25, 0x1c00
	s_add_i32 s0, s0, s28
	s_mulk_i32 s25, 0x1c00
	s_waitcnt lgkmcnt(0)
	s_add_u32 s1, s88, s25
	ds_read_b128 v[2:5], v199
	s_addc_u32 s2, s89, s0
	s_lshl_b32 s0, s34, 1
	s_add_u32 s0, s1, s0
	s_mulk_i32 s29, 0x1200
	s_addc_u32 s1, s2, 0
	s_add_i32 s2, s29, 0
	s_add_i32 s2, s2, 0x15800
	s_cmpk_gt_i32 s8, 0x7ff
	s_cbranch_scc0 .Lepi_gates_done
	v_lshlrev_b32_e32 v146, 1, v196
	v_mov_b32_e32 v147, 0
	s_mov_b64 s[14:15], 0x1000
	v_lshl_add_u64 v[146:147], s[0:1], 0, v[146:147]
	v_lshrrev_b32_e32 v148, 3, v191
	v_lshl_add_u64 v[146:147], v[146:147], 0, s[14:15]
	v_or_b32_e32 v148, s24, v148
	v_mad_i64_i32 v[150:151], s[16:17], v148, s13, v[146:147]
	v_or_b32_e32 v149, 8, v148
	global_load_dwordx4 v[130:133], v[150:151], off
	v_mad_i64_i32 v[152:153], s[16:17], v149, s13, v[146:147]
	v_or_b32_e32 v149, 16, v148
	global_load_dwordx4 v[134:137], v[152:153], off
	v_mad_i64_i32 v[150:151], s[16:17], v149, s13, v[146:147]
	v_or_b32_e32 v149, 24, v148
	global_load_dwordx4 v[138:141], v[150:151], off
	v_mad_i64_i32 v[152:153], s[16:17], v149, s13, v[146:147]
	s_nop 0
	global_load_dwordx4 v[142:145], v[152:153], off
.Lepi_gates_done:
	s_waitcnt lgkmcnt(1)
	v_lshlrev_b32_e32 v0, 1, v198
	v_mul_u32_u24_e32 v6, 0x240, v197
	v_add3_u32 v0, s2, v0, v6
	s_waitcnt lgkmcnt(0)
	v_mul_f32_e32 v6, v34, v2
	v_mul_f32_e32 v2, v50, v2
	v_cvt_pk_bf16_f32 v2, v2, s0
	ds_write_b16 v0, v2 offset:64
	v_mul_f32_e32 v2, v35, v3
	v_cvt_pk_bf16_f32 v2, v2, s0
	ds_write_b16 v0, v2 offset:144
	v_mul_f32_e32 v2, v51, v3
	v_cvt_pk_bf16_f32 v2, v2, s0
	ds_write_b16 v0, v2 offset:208
	v_mul_f32_e32 v2, v36, v4
	v_cvt_pk_bf16_f32 v2, v2, s0
	ds_write_b16 v0, v2 offset:288
	v_mul_f32_e32 v2, v52, v4
	v_cvt_pk_bf16_f32 v2, v2, s0
	ds_write_b16 v0, v2 offset:352
	v_mul_f32_e32 v2, v37, v5
	v_cvt_pk_bf16_f32 v2, v2, s0
	ds_write_b16 v0, v2 offset:432
	v_mul_f32_e32 v2, v53, v5
	v_cvt_pk_bf16_f32 v6, v6, s0
	v_cvt_pk_bf16_f32 v2, v2, s0
	ds_write_b16 v0, v6
	ds_write_b16 v0, v2 offset:496
	ds_read_b128 v[2:5], v199 offset:32
	s_waitcnt lgkmcnt(0)
	v_mul_f32_e32 v6, v38, v2
	v_mul_f32_e32 v2, v54, v2
	v_cvt_pk_bf16_f32 v2, v2, s0
	ds_write_b16 v0, v2 offset:1216
	v_mul_f32_e32 v2, v39, v3
	v_cvt_pk_bf16_f32 v2, v2, s0
	ds_write_b16 v0, v2 offset:1296
	v_mul_f32_e32 v2, v55, v3
	v_cvt_pk_bf16_f32 v2, v2, s0
	ds_write_b16 v0, v2 offset:1360
	v_mul_f32_e32 v2, v40, v4
	v_cvt_pk_bf16_f32 v2, v2, s0
	ds_write_b16 v0, v2 offset:1440
	v_mul_f32_e32 v2, v56, v4
	v_cvt_pk_bf16_f32 v2, v2, s0
	ds_write_b16 v0, v2 offset:1504
	v_mul_f32_e32 v2, v41, v5
	v_cvt_pk_bf16_f32 v2, v2, s0
	ds_write_b16 v0, v2 offset:1584
	v_mul_f32_e32 v2, v57, v5
	v_cvt_pk_bf16_f32 v6, v6, s0
	v_cvt_pk_bf16_f32 v2, v2, s0
	ds_write_b16 v0, v6 offset:1152
	ds_write_b16 v0, v2 offset:1648
	ds_read_b128 v[2:5], v199 offset:64
	s_waitcnt lgkmcnt(0)
	v_mul_f32_e32 v6, v42, v2
	v_mul_f32_e32 v2, v58, v2
	v_cvt_pk_bf16_f32 v2, v2, s0
	ds_write_b16 v0, v2 offset:2368
	v_mul_f32_e32 v2, v43, v3
	v_cvt_pk_bf16_f32 v2, v2, s0
	ds_write_b16 v0, v2 offset:2448
	v_mul_f32_e32 v2, v59, v3
	v_cvt_pk_bf16_f32 v2, v2, s0
	ds_write_b16 v0, v2 offset:2512
	v_mul_f32_e32 v2, v44, v4
	v_cvt_pk_bf16_f32 v2, v2, s0
	ds_write_b16 v0, v2 offset:2592
	v_mul_f32_e32 v2, v60, v4
	v_cvt_pk_bf16_f32 v2, v2, s0
	ds_write_b16 v0, v2 offset:2656
	v_mul_f32_e32 v2, v45, v5
	v_cvt_pk_bf16_f32 v2, v2, s0
	ds_write_b16 v0, v2 offset:2736
	v_mul_f32_e32 v2, v61, v5
	v_cvt_pk_bf16_f32 v6, v6, s0
	v_cvt_pk_bf16_f32 v2, v2, s0
	ds_write_b16 v0, v6 offset:2304
	ds_write_b16 v0, v2 offset:2800
	ds_read_b128 v[2:5], v199 offset:96
	s_waitcnt lgkmcnt(0)
	v_mul_f32_e32 v6, v46, v2
	v_mul_f32_e32 v2, v62, v2
	v_cvt_pk_bf16_f32 v2, v2, s0
	ds_write_b16 v0, v2 offset:3520
	v_mul_f32_e32 v2, v47, v3
	v_cvt_pk_bf16_f32 v2, v2, s0
	ds_write_b16 v0, v2 offset:3600
	v_mul_f32_e32 v2, v63, v3
	v_cvt_pk_bf16_f32 v2, v2, s0
	ds_write_b16 v0, v2 offset:3664
	v_mul_f32_e32 v2, v48, v4
	v_cvt_pk_bf16_f32 v2, v2, s0
	ds_write_b16 v0, v2 offset:3744
	v_mul_f32_e32 v2, v64, v4
	v_cvt_pk_bf16_f32 v2, v2, s0
	ds_write_b16 v0, v2 offset:3808
	v_mul_f32_e32 v2, v49, v5
	v_cvt_pk_bf16_f32 v2, v2, s0
	ds_write_b16 v0, v2 offset:3888
	v_mul_f32_e32 v2, v65, v5
	v_cvt_pk_bf16_f32 v6, v6, s0
	v_cvt_pk_bf16_f32 v2, v2, s0
	ds_write_b16 v0, v6 offset:3456
	ds_write_b16 v0, v2 offset:3952
	v_lshlrev_b32_e32 v0, 1, v196
	v_lshl_add_u64 v[2:3], s[0:1], 0, v[0:1]
	s_mov_b64 s[0:1], 0x1000
	v_lshrrev_b32_e32 v0, 3, v191
	v_lshl_add_u64 v[2:3], v[2:3], 0, s[0:1]
	v_or_b32_e32 v18, s24, v0
	s_waitcnt lgkmcnt(0)
; #define LAS __attribute__((address_space(3)))
; __device__ __forceinline__ unsigned cvtpk(float lo, float hi) { f32x2 v = {lo, hi}; bf16x2_t b = __builtin_convertvector(v, bf16x2_t); return __builtin_bit_cast(unsigned, b); }
; __device__ __forceinline__ float bflo(unsigned u) { return __uint_as_float(u << 16); }
; __device__ __forceinline__ float bfhi(unsigned u) { return __uint_as_float(u & 0xffff0000u); }
; __device__ __forceinline__ void attn_unit(LAS char* lds, const bf16_t* Qp, const bf16_t* KVp, const bf16_t* KRp, int ntiles, bf16_t* Yp, bool dry) {
;     ...
;     for (int i = 0; i < 4; ++i) { const int id = lane + 64 * i, row = id >> 3, ch = id & 7;
;         const u32x4 ov = *(const LAS u32x4*)(ost + row * A_OP + ch * 16);
;         bf16_t* yp = Yp + (size_t)(wid * 32 + row) * ZP + ch * 8;
;         if (!dry) { const u32x4 gv = *(const u32x4*)yp; u32x4 w;
;             w.x = cvtpk(bflo(ov.x) * bflo(gv.x), bfhi(ov.x) * bfhi(gv.x)); w.y = cvtpk(bflo(ov.y) * bflo(gv.y), bfhi(ov.y) * bfhi(gv.y));
;             w.z = cvtpk(bflo(ov.z) * bflo(gv.z), bfhi(ov.z) * bfhi(gv.z)); w.w = cvtpk(bflo(ov.w) * bflo(gv.w), bfhi(ov.w) * bfhi(gv.w));
;             *(u32x4*)yp = w; } }
	v_mad_i64_i32 v[12:13], s[0:1], v18, s13, v[2:3]
	s_nop 0
	v_mul_u32_u24_e32 v0, 0x90, v0
	v_add3_u32 v0, s2, v188, v0
	ds_read_b128 v[4:7], v0
	s_waitcnt lgkmcnt(0)
	v_lshlrev_b32_e32 v14, 16, v4
	v_and_b32_e32 v15, 0xffff0000, v4
	s_waitcnt vmcnt(0)
	v_mov_b64_e32 v[8:9], v[130:131]
	v_mov_b64_e32 v[10:11], v[132:133]
	v_lshlrev_b32_e32 v16, 16, v8
	v_and_b32_e32 v17, 0xffff0000, v8
	v_pk_mul_f32 v[14:15], v[14:15], v[16:17]
	v_lshlrev_b32_e32 v8, 16, v9
	v_cvt_pk_bf16_f32 v4, v14, v15
	v_lshlrev_b32_e32 v14, 16, v5
	v_and_b32_e32 v15, 0xffff0000, v5
	v_and_b32_e32 v9, 0xffff0000, v9
	v_pk_mul_f32 v[8:9], v[14:15], v[8:9]
	v_lshlrev_b32_e32 v14, 16, v10
	v_cvt_pk_bf16_f32 v5, v8, v9
	v_lshlrev_b32_e32 v8, 16, v6
	v_and_b32_e32 v9, 0xffff0000, v6
	v_and_b32_e32 v15, 0xffff0000, v10
	v_pk_mul_f32 v[8:9], v[8:9], v[14:15]
	v_lshlrev_b32_e32 v10, 16, v11
	v_cvt_pk_bf16_f32 v6, v8, v9
	v_lshlrev_b32_e32 v8, 16, v7
	v_and_b32_e32 v9, 0xffff0000, v7
	v_and_b32_e32 v11, 0xffff0000, v11
	v_pk_mul_f32 v[8:9], v[8:9], v[10:11]
	s_nop 0
	v_cvt_pk_bf16_f32 v7, v8, v9
	global_store_dwordx4 v[12:13], v[4:7], off
	s_nop 1
	v_or_b32_e32 v4, 8, v18
	v_mad_i64_i32 v[12:13], s[0:1], v4, s13, v[2:3]
	s_nop 0
	ds_read_b128 v[4:7], v0 offset:1152
	s_waitcnt lgkmcnt(0)
	v_lshlrev_b32_e32 v14, 16, v4
	v_and_b32_e32 v15, 0xffff0000, v4
	v_mov_b64_e32 v[8:9], v[134:135]
	v_mov_b64_e32 v[10:11], v[136:137]
	v_lshlrev_b32_e32 v16, 16, v8
	v_and_b32_e32 v17, 0xffff0000, v8
	v_pk_mul_f32 v[14:15], v[14:15], v[16:17]
	v_lshlrev_b32_e32 v8, 16, v9
	v_cvt_pk_bf16_f32 v4, v14, v15
	v_lshlrev_b32_e32 v14, 16, v5
	v_and_b32_e32 v15, 0xffff0000, v5
	v_and_b32_e32 v9, 0xffff0000, v9
	v_pk_mul_f32 v[8:9], v[14:15], v[8:9]
	v_lshlrev_b32_e32 v14, 16, v10
	v_cvt_pk_bf16_f32 v5, v8, v9
	v_lshlrev_b32_e32 v8, 16, v6
	v_and_b32_e32 v9, 0xffff0000, v6
	v_and_b32_e32 v15, 0xffff0000, v10
	v_pk_mul_f32 v[8:9], v[8:9], v[14:15]
	v_lshlrev_b32_e32 v10, 16, v11
	v_cvt_pk_bf16_f32 v6, v8, v9
	v_lshlrev_b32_e32 v8, 16, v7
	v_and_b32_e32 v9, 0xffff0000, v7
	v_and_b32_e32 v11, 0xffff0000, v11
	v_pk_mul_f32 v[8:9], v[8:9], v[10:11]
	s_nop 0
	v_cvt_pk_bf16_f32 v7, v8, v9
	global_store_dwordx4 v[12:13], v[4:7], off
	s_nop 1
	v_or_b32_e32 v4, 16, v18
	v_mad_i64_i32 v[12:13], s[0:1], v4, s13, v[2:3]
	s_nop 0
	ds_read_b128 v[4:7], v0 offset:2304
	s_waitcnt lgkmcnt(0)
	v_lshlrev_b32_e32 v14, 16, v4
	v_and_b32_e32 v15, 0xffff0000, v4
	v_mov_b64_e32 v[8:9], v[138:139]
	v_mov_b64_e32 v[10:11], v[140:141]
	v_lshlrev_b32_e32 v16, 16, v8
	v_and_b32_e32 v17, 0xffff0000, v8
	v_pk_mul_f32 v[14:15], v[14:15], v[16:17]
	v_lshlrev_b32_e32 v8, 16, v9
	v_cvt_pk_bf16_f32 v4, v14, v15
	v_lshlrev_b32_e32 v14, 16, v5
	v_and_b32_e32 v15, 0xffff0000, v5
	v_and_b32_e32 v9, 0xffff0000, v9
	v_pk_mul_f32 v[8:9], v[14:15], v[8:9]
	v_lshlrev_b32_e32 v14, 16, v10
	v_cvt_pk_bf16_f32 v5, v8, v9
	v_lshlrev_b32_e32 v8, 16, v6
	v_and_b32_e32 v9, 0xffff0000, v6
	v_and_b32_e32 v15, 0xffff0000, v10
	v_pk_mul_f32 v[8:9], v[8:9], v[14:15]
	v_lshlrev_b32_e32 v10, 16, v11
	v_cvt_pk_bf16_f32 v6, v8, v9
	v_lshlrev_b32_e32 v8, 16, v7
	v_and_b32_e32 v9, 0xffff0000, v7
	v_and_b32_e32 v11, 0xffff0000, v11
	v_pk_mul_f32 v[8:9], v[8:9], v[10:11]
	s_nop 0
	v_cvt_pk_bf16_f32 v7, v8, v9
	global_store_dwordx4 v[12:13], v[4:7], off
	s_nop 1
	v_or_b32_e32 v4, 24, v18
	v_mad_i64_i32 v[10:11], s[0:1], v4, s13, v[2:3]
	s_nop 0
	ds_read_b128 v[2:5], v0 offset:3456
	s_waitcnt lgkmcnt(0)
	v_lshlrev_b32_e32 v12, 16, v2
	v_and_b32_e32 v13, 0xffff0000, v2
	v_mov_b64_e32 v[6:7], v[142:143]
	v_mov_b64_e32 v[8:9], v[144:145]
	v_lshlrev_b32_e32 v14, 16, v6
	v_and_b32_e32 v15, 0xffff0000, v6
	v_pk_mul_f32 v[12:13], v[12:13], v[14:15]
	v_lshlrev_b32_e32 v6, 16, v7
	v_cvt_pk_bf16_f32 v2, v12, v13
	v_lshlrev_b32_e32 v12, 16, v3
	v_and_b32_e32 v13, 0xffff0000, v3
	v_and_b32_e32 v7, 0xffff0000, v7
	v_pk_mul_f32 v[6:7], v[12:13], v[6:7]
	v_lshlrev_b32_e32 v12, 16, v8
	v_cvt_pk_bf16_f32 v3, v6, v7
	v_lshlrev_b32_e32 v6, 16, v4
	v_and_b32_e32 v7, 0xffff0000, v4
	v_and_b32_e32 v13, 0xffff0000, v8
	v_pk_mul_f32 v[6:7], v[6:7], v[12:13]
	v_lshlrev_b32_e32 v8, 16, v9
	v_cvt_pk_bf16_f32 v4, v6, v7
	v_lshlrev_b32_e32 v6, 16, v5
	v_and_b32_e32 v7, 0xffff0000, v5
	v_and_b32_e32 v9, 0xffff0000, v9
	v_pk_mul_f32 v[6:7], v[6:7], v[8:9]
	s_nop 0
	v_cvt_pk_bf16_f32 v5, v6, v7
	global_store_dwordx4 v[10:11], v[2:5], off
	s_barrier

; __device__ __forceinline__ void attn_unit(LAS char* lds, const bf16_t* Qp, const bf16_t* KVp, const bf16_t* KRp, int ntiles, bf16_t* Yp, bool dry) {
;     ...
;         if (!dry) { const u32x4 gv = *(const u32x4*)yp; u32x4 w;
.Latt_noload:
	ds_read_b128 v[66:69], v0 offset:0
	ds_read_b128 v[70:73], v0 offset:6656
	ds_read_b128 v[74:77], v0 offset:32
	ds_read_b128 v[78:81], v0 offset:6688
	ds_read_b128 v[212:215], v0 offset:64
	ds_read_b128 v[240:243], v0 offset:6720
	ds_read_b128 v[244:247], v0 offset:96
	s_waitcnt lgkmcnt(6)
	v_mfma_f32_32x32x16_bf16 v[114:129], v[66:69], v[154:157], v[82:97]
	ds_read_b128 v[248:251], v0 offset:6752
	s_waitcnt lgkmcnt(6)
	v_mfma_f32_32x32x16_bf16 v[98:113], v[70:73], v[154:157], v[82:97]
	ds_read_b128 v[66:69], v0 offset:128
	s_waitcnt lgkmcnt(6)
	v_mfma_f32_32x32x16_bf16 v[114:129], v[74:77], v[158:161], v[114:129]
	ds_read_b128 v[70:73], v0 offset:6784
	s_waitcnt lgkmcnt(6)
	v_mfma_f32_32x32x16_bf16 v[98:113], v[78:81], v[158:161], v[98:113]
	ds_read_b128 v[74:77], v0 offset:160
	s_waitcnt lgkmcnt(6)
	v_mfma_f32_32x32x16_bf16 v[114:129], v[212:215], v[162:165], v[114:129]
	ds_read_b128 v[78:81], v0 offset:6816
	s_waitcnt lgkmcnt(6)
	v_mfma_f32_32x32x16_bf16 v[98:113], v[240:243], v[162:165], v[98:113]
	ds_read_b128 v[212:215], v0 offset:13312
	s_waitcnt lgkmcnt(6)
	v_mfma_f32_32x32x16_bf16 v[114:129], v[244:247], v[166:169], v[114:129]
	ds_read_b128 v[240:243], v0 offset:19968
	s_waitcnt lgkmcnt(6)
	v_mfma_f32_32x32x16_bf16 v[98:113], v[248:251], v[166:169], v[98:113]
	ds_read_b128 v[244:247], v0 offset:13344
	s_waitcnt lgkmcnt(6)
	v_mfma_f32_32x32x16_bf16 v[114:129], v[66:69], v[170:173], v[114:129]
	ds_read_b128 v[248:251], v0 offset:20000
	s_waitcnt lgkmcnt(6)
	v_mfma_f32_32x32x16_bf16 v[98:113], v[70:73], v[170:173], v[98:113]
	ds_read_b128 v[66:69], v0 offset:13376
	s_waitcnt lgkmcnt(6)
	v_mfma_f32_32x32x16_bf16 v[114:129], v[74:77], v[174:177], v[114:129]
	ds_read_b128 v[70:73], v0 offset:20032
	s_waitcnt lgkmcnt(6)
	v_mfma_f32_32x32x16_bf16 v[98:113], v[78:81], v[174:177], v[98:113]
	ds_read_b128 v[74:77], v0 offset:13408
	s_waitcnt lgkmcnt(6)
	v_mfma_f32_32x32x16_bf16 v[2:17], v[212:215], v[154:157], v[82:97]
	ds_read_b128 v[78:81], v0 offset:20064
	s_waitcnt lgkmcnt(6)
	v_mfma_f32_32x32x16_bf16 v[18:33], v[240:243], v[154:157], v[82:97]
	ds_read_b128 v[212:215], v0 offset:13440
	s_waitcnt lgkmcnt(6)
	v_mfma_f32_32x32x16_bf16 v[2:17], v[244:247], v[158:161], v[2:17]
	ds_read_b128 v[240:243], v0 offset:20096
	s_waitcnt lgkmcnt(6)
	v_mfma_f32_32x32x16_bf16 v[18:33], v[248:251], v[158:161], v[18:33]
	ds_read_b128 v[244:247], v0 offset:13472
	s_waitcnt lgkmcnt(6)
	v_mfma_f32_32x32x16_bf16 v[2:17], v[66:69], v[162:165], v[2:17]
	ds_read_b128 v[248:251], v0 offset:20128
	s_waitcnt lgkmcnt(6)
	v_mfma_f32_32x32x16_bf16 v[18:33], v[70:73], v[162:165], v[18:33]
	ds_read_b64_tr_b16 v[216:217], v185 offset:53248
	ds_read_b64_tr_b16 v[218:219], v185 offset:53760
	s_waitcnt lgkmcnt(7)
	v_mfma_f32_32x32x16_bf16 v[2:17], v[74:77], v[166:169], v[2:17]
	ds_read_b64_tr_b16 v[220:221], v185 offset:57344
	ds_read_b64_tr_b16 v[222:223], v185 offset:57856
	s_waitcnt lgkmcnt(8)
	v_mfma_f32_32x32x16_bf16 v[18:33], v[78:81], v[166:169], v[18:33]
	ds_read_b64_tr_b16 v[224:225], v185 offset:54272
	ds_read_b64_tr_b16 v[226:227], v185 offset:54784
	s_waitcnt lgkmcnt(9)
	v_mfma_f32_32x32x16_bf16 v[2:17], v[212:215], v[170:173], v[2:17]
	ds_read_b64_tr_b16 v[228:229], v185 offset:58368
	ds_read_b64_tr_b16 v[230:231], v185 offset:58880
	s_waitcnt lgkmcnt(10)
	v_mfma_f32_32x32x16_bf16 v[18:33], v[240:243], v[170:173], v[18:33]
	ds_read_b64_tr_b16 v[232:233], v185 offset:55296
	ds_read_b64_tr_b16 v[234:235], v185 offset:55808
	s_waitcnt lgkmcnt(11)
	v_mfma_f32_32x32x16_bf16 v[2:17], v[244:247], v[174:177], v[2:17]
	ds_read_b64_tr_b16 v[236:237], v185 offset:59392
	ds_read_b64_tr_b16 v[238:239], v185 offset:59904
	s_waitcnt lgkmcnt(12)
	v_mfma_f32_32x32x16_bf16 v[18:33], v[248:251], v[174:177], v[18:33]
	s_cmp_lg_u32 s35, 34
	s_cbranch_scc1 .Latt_nogate
	s_mul_i32 s14, s28, 0x1c00
	s_mul_hi_u32 s15, s25, 0x1c00
	s_add_i32 s15, s15, s14
	s_mul_i32 s14, s25, 0x1c00
	s_add_u32 s14, s88, s14
	s_addc_u32 s15, s89, s15
	s_lshl_b32 s2, s34, 1
	s_add_u32 s14, s14, s2
	s_addc_u32 s15, s15, 0
	v_lshlrev_b32_e32 v146, 1, v196
	v_mov_b32_e32 v147, 0
	s_mov_b64 s[2:3], 0x1000
	v_lshl_add_u64 v[146:147], s[14:15], 0, v[146:147]
	v_lshrrev_b32_e32 v148, 3, v191
	v_lshl_add_u64 v[146:147], v[146:147], 0, s[2:3]
	v_or_b32_e32 v148, s24, v148
	v_mad_i64_i32 v[150:151], s[16:17], v148, s13, v[146:147]
	v_or_b32_e32 v149, 8, v148
	global_load_dwordx4 v[130:133], v[150:151], off
	v_mad_i64_i32 v[152:153], s[16:17], v149, s13, v[146:147]
	v_or_b32_e32 v149, 16, v148
	global_load_dwordx4 v[134:137], v[152:153], off
	v_mad_i64_i32 v[150:151], s[16:17], v149, s13, v[146:147]
	v_or_b32_e32 v149, 24, v148
	global_load_dwordx4 v[138:141], v[150:151], off
	v_mad_i64_i32 v[152:153], s[16:17], v149, s13, v[146:147]
	s_nop 0
	global_load_dwordx4 v[142:145], v[152:153], off
.Latt_nogate:
	v_exp_f32_e32 v114, v114
	v_exp_f32_e32 v115, v115
	v_exp_f32_e32 v116, v116
	v_exp_f32_e32 v117, v117
	v_exp_f32_e32 v118, v118
	v_exp_f32_e32 v119, v119
	v_exp_f32_e32 v120, v120
	v_exp_f32_e32 v121, v121
	v_cvt_pk_bf16_f32 v66, v114, v115
	v_cvt_pk_bf16_f32 v67, v116, v117
	v_cvt_pk_bf16_f32 v68, v118, v119
	v_cvt_pk_bf16_f32 v69, v120, v121
	v_add_f32_e32 v178, v114, v115
	v_add_f32_e32 v179, v116, v117
	v_add_f32_e32 v180, v118, v119
	v_add_f32_e32 v181, v120, v121
	v_add_f32_e32 v178, v178, v179
	v_add_f32_e32 v180, v180, v181
	v_add_f32_e32 v178, v178, v180
	v_add_f32_e32 v210, v210, v178
	ds_read_b64_tr_b16 v[240:241], v185 offset:56320
	ds_read_b64_tr_b16 v[242:243], v185 offset:56832
	ds_read_b64_tr_b16 v[244:245], v185 offset:60416
	s_waitcnt lgkmcnt(11)
	ds_read_b64_tr_b16 v[246:247], v185 offset:60928
	ds_read_b64_tr_b16 v[114:115], v184 offset:53248
	ds_read_b64_tr_b16 v[116:117], v184 offset:53760
	ds_read_b64_tr_b16 v[118:119], v184 offset:57344
	s_waitcnt lgkmcnt(11)
	ds_read_b64_tr_b16 v[120:121], v184 offset:57856
	v_exp_f32_e32 v122, v122
	v_exp_f32_e32 v123, v123
	v_exp_f32_e32 v124, v124
	v_mfma_f32_32x32x16_bf16 v[34:49], v[66:69], v[216:219], v[34:49]
	v_exp_f32_e32 v125, v125
	v_exp_f32_e32 v126, v126
	v_exp_f32_e32 v127, v127
	v_exp_f32_e32 v128, v128
	v_exp_f32_e32 v129, v129
	v_cvt_pk_bf16_f32 v70, v122, v123
	v_cvt_pk_bf16_f32 v71, v124, v125
	v_mfma_f32_32x32x16_bf16 v[50:65], v[66:69], v[220:223], v[50:65]
	v_cvt_pk_bf16_f32 v72, v126, v127
	v_cvt_pk_bf16_f32 v73, v128, v129
	v_add_f32_e32 v178, v122, v123
	v_add_f32_e32 v179, v124, v125
	v_add_f32_e32 v180, v126, v127
	v_add_f32_e32 v181, v128, v129
	v_add_f32_e32 v178, v178, v179
	v_add_f32_e32 v180, v180, v181
	v_add_f32_e32 v178, v178, v180
	v_add_f32_e32 v210, v210, v178
	ds_read_b64_tr_b16 v[122:123], v184 offset:54272
	ds_read_b64_tr_b16 v[124:125], v184 offset:54784
	ds_read_b64_tr_b16 v[126:127], v184 offset:58368
	s_waitcnt lgkmcnt(11)
	ds_read_b64_tr_b16 v[128:129], v184 offset:58880
	v_exp_f32_e32 v98, v98
	v_exp_f32_e32 v99, v99
	v_exp_f32_e32 v100, v100
	v_mfma_f32_32x32x16_bf16 v[34:49], v[70:73], v[224:227], v[34:49]
	v_exp_f32_e32 v101, v101
	v_exp_f32_e32 v102, v102
	v_exp_f32_e32 v103, v103
	v_exp_f32_e32 v104, v104
	v_exp_f32_e32 v105, v105
	v_cvt_pk_bf16_f32 v74, v98, v99
	v_cvt_pk_bf16_f32 v75, v100, v101
	v_mfma_f32_32x32x16_bf16 v[50:65], v[70:73], v[228:231], v[50:65]
	v_cvt_pk_bf16_f32 v76, v102, v103
	v_cvt_pk_bf16_f32 v77, v104, v105
	v_add_f32_e32 v178, v98, v99
	v_add_f32_e32 v179, v100, v101
	v_add_f32_e32 v180, v102, v103
	v_add_f32_e32 v181, v104, v105
	v_add_f32_e32 v178, v178, v179
	v_add_f32_e32 v180, v180, v181
	v_add_f32_e32 v178, v178, v180
	v_add_f32_e32 v210, v210, v178
	ds_read_b64_tr_b16 v[98:99], v184 offset:55296
	ds_read_b64_tr_b16 v[100:101], v184 offset:55808
	ds_read_b64_tr_b16 v[102:103], v184 offset:59392
	s_waitcnt lgkmcnt(11)
	ds_read_b64_tr_b16 v[104:105], v184 offset:59904
	v_exp_f32_e32 v106, v106
	v_exp_f32_e32 v107, v107
	v_exp_f32_e32 v108, v108
	v_mfma_f32_32x32x16_bf16 v[34:49], v[74:77], v[232:235], v[34:49]
	v_exp_f32_e32 v109, v109
	v_exp_f32_e32 v110, v110
	v_exp_f32_e32 v111, v111
	v_exp_f32_e32 v112, v112
	v_exp_f32_e32 v113, v113
	v_cvt_pk_bf16_f32 v78, v106, v107
	v_cvt_pk_bf16_f32 v79, v108, v109
	v_mfma_f32_32x32x16_bf16 v[50:65], v[74:77], v[236:239], v[50:65]
	v_cvt_pk_bf16_f32 v80, v110, v111
	v_cvt_pk_bf16_f32 v81, v112, v113
	v_add_f32_e32 v178, v106, v107
	v_add_f32_e32 v179, v108, v109
	v_add_f32_e32 v180, v110, v111
	v_add_f32_e32 v181, v112, v113
	v_add_f32_e32 v178, v178, v179
	v_add_f32_e32 v180, v180, v181
	v_add_f32_e32 v178, v178, v180
	v_add_f32_e32 v210, v210, v178
	ds_read_b64_tr_b16 v[106:107], v184 offset:56320
	ds_read_b64_tr_b16 v[108:109], v184 offset:56832
	ds_read_b64_tr_b16 v[110:111], v184 offset:60416
	s_waitcnt lgkmcnt(11)
	ds_read_b64_tr_b16 v[112:113], v184 offset:60928
	v_exp_f32_e32 v2, v2
	v_exp_f32_e32 v3, v3
	v_exp_f32_e32 v4, v4
	v_mfma_f32_32x32x16_bf16 v[34:49], v[78:81], v[240:243], v[34:49]
	v_exp_f32_e32 v5, v5
	v_exp_f32_e32 v6, v6
	v_exp_f32_e32 v7, v7
	v_exp_f32_e32 v8, v8
	v_exp_f32_e32 v9, v9
	v_cvt_pk_bf16_f32 v66, v2, v3
	v_cvt_pk_bf16_f32 v67, v4, v5
	v_mfma_f32_32x32x16_bf16 v[50:65], v[78:81], v[244:247], v[50:65]
	v_cvt_pk_bf16_f32 v68, v6, v7
	v_cvt_pk_bf16_f32 v69, v8, v9
	v_add_f32_e32 v178, v2, v3
	v_add_f32_e32 v179, v4, v5
	v_add_f32_e32 v180, v6, v7
	v_add_f32_e32 v181, v8, v9
	v_add_f32_e32 v178, v178, v179
	v_add_f32_e32 v180, v180, v181
	v_add_f32_e32 v178, v178, v180
	v_add_f32_e32 v210, v210, v178
	v_exp_f32_e32 v10, v10
	v_exp_f32_e32 v11, v11
	v_exp_f32_e32 v12, v12
	v_mfma_f32_32x32x16_bf16 v[34:49], v[66:69], v[114:117], v[34:49]
	v_exp_f32_e32 v13, v13
	v_exp_f32_e32 v14, v14
	v_exp_f32_e32 v15, v15
	v_exp_f32_e32 v16, v16
	v_exp_f32_e32 v17, v17
	v_cvt_pk_bf16_f32 v70, v10, v11
	v_cvt_pk_bf16_f32 v71, v12, v13
	v_mfma_f32_32x32x16_bf16 v[50:65], v[66:69], v[118:121], v[50:65]
	v_cvt_pk_bf16_f32 v72, v14, v15
	v_cvt_pk_bf16_f32 v73, v16, v17
	v_add_f32_e32 v178, v10, v11
	v_add_f32_e32 v179, v12, v13
	v_add_f32_e32 v180, v14, v15
	v_add_f32_e32 v181, v16, v17
	v_add_f32_e32 v178, v178, v179
	v_add_f32_e32 v180, v180, v181
	v_add_f32_e32 v178, v178, v180
	v_add_f32_e32 v210, v210, v178
	v_exp_f32_e32 v18, v18
	v_exp_f32_e32 v19, v19
	v_exp_f32_e32 v20, v20
	s_waitcnt lgkmcnt(10)
	v_mfma_f32_32x32x16_bf16 v[34:49], v[70:73], v[122:125], v[34:49]
	v_exp_f32_e32 v21, v21
	v_exp_f32_e32 v22, v22
	v_exp_f32_e32 v23, v23
	v_exp_f32_e32 v24, v24
	v_exp_f32_e32 v25, v25
	v_cvt_pk_bf16_f32 v74, v18, v19
	v_cvt_pk_bf16_f32 v75, v20, v21
	s_waitcnt lgkmcnt(8)
	v_mfma_f32_32x32x16_bf16 v[50:65], v[70:73], v[126:129], v[50:65]
	v_cvt_pk_bf16_f32 v76, v22, v23
	v_cvt_pk_bf16_f32 v77, v24, v25
	v_add_f32_e32 v178, v18, v19
	v_add_f32_e32 v179, v20, v21
	v_add_f32_e32 v180, v22, v23
	v_add_f32_e32 v181, v24, v25
	v_add_f32_e32 v178, v178, v179
	v_add_f32_e32 v180, v180, v181
	v_add_f32_e32 v178, v178, v180
	v_add_f32_e32 v210, v210, v178
	v_exp_f32_e32 v26, v26
	v_exp_f32_e32 v27, v27
	v_exp_f32_e32 v28, v28
	s_waitcnt lgkmcnt(6)
	v_mfma_f32_32x32x16_bf16 v[34:49], v[74:77], v[98:101], v[34:49]
	v_exp_f32_e32 v29, v29
	v_exp_f32_e32 v30, v30
	v_exp_f32_e32 v31, v31
	v_exp_f32_e32 v32, v32
	v_exp_f32_e32 v33, v33
	v_cvt_pk_bf16_f32 v78, v26, v27
	v_cvt_pk_bf16_f32 v79, v28, v29
	s_waitcnt lgkmcnt(4)
	v_mfma_f32_32x32x16_bf16 v[50:65], v[74:77], v[102:105], v[50:65]
	v_cvt_pk_bf16_f32 v80, v30, v31
	v_cvt_pk_bf16_f32 v81, v32, v33
	v_add_f32_e32 v178, v26, v27
	v_add_f32_e32 v179, v28, v29
	v_add_f32_e32 v180, v30, v31
	v_add_f32_e32 v181, v32, v33
	v_add_f32_e32 v178, v178, v179
	v_add_f32_e32 v180, v180, v181
	v_add_f32_e32 v178, v178, v180
	v_add_f32_e32 v210, v210, v178
	s_waitcnt lgkmcnt(2)
	v_mfma_f32_32x32x16_bf16 v[34:49], v[78:81], v[106:109], v[34:49]
	s_waitcnt lgkmcnt(0)
	v_mfma_f32_32x32x16_bf16 v[50:65], v[78:81], v[110:113], v[50:65]
	s_cmp_eq_u32 s35, 0
	s_cbranch_scc1 .Latt_rs
	v_cmp_lt_f32_e32 vcc, 0x4b800000, v210
	s_cbranch_vccnz .Latt_rs
